# phase 0 adaLN modulation GEMV on the f32 matrix cores (v_mfma_f32_32x32x2_f32, f32 operands and accumulate), silu(c) staged transposed in LDS
# speedup vs baseline: 1.0184x; 1.0184x over previous
.LBB0_442:
	s_andn2_b64 vcc, exec, s[12:13]
	s_mov_b32 s28, 0xb000
	s_mov_b32 s30, 0x20000
	s_mov_b32 s29, 0x22000
	s_mov_b32 s31, 0x24000
	s_mov_b32 s42, 0x26000
	s_mov_b32 s43, 0x28000
	s_waitcnt lgkmcnt(0)
	s_mov_b32 s48, 0x2a000
	s_mov_b32 s49, 0x2c000
	s_mov_b32 s50, 0x2e000
	s_mov_b32 s51, 0x30000
	s_mov_b32 s52, 0x32000
	s_mov_b32 s53, 0x34000
	s_mov_b32 s54, 0x36000
	s_mov_b32 s56, 0x38000
	s_mov_b32 s64, 0x3a000
	s_mov_b32 s65, 0x3c000
	s_cbranch_vccnz .LBB0_8
	v_mov_b32_e32 v2, v163
	s_mov_b32 s2, s75
	v_cmp_gt_i32_e32 vcc, s70, v2
	s_and_saveexec_b64 s[10:11], vcc
	s_cbranch_execz .LBB0_446
	s_load_dwordx2 s[8:9], s[0:1], 0x8
	v_ashrrev_i32_e32 v3, 31, v2
	v_add_u32_e32 v1, 0xfffffe00, v2
	v_mul_u32_u24_e32 v6, 0x84, v2
	v_add_u32_e32 v208, 0x10800, v6
	s_mov_b64 s[12:13], 0
	s_waitcnt lgkmcnt(0)
	v_lshl_add_u64 v[4:5], v[2:3], 2, s[8:9]

.Lsilu_pass:
	global_load_dword v176, v[4:5], off
	v_lshl_add_u64 v[4:5], v[4:5], 0, s[8:9]
	global_load_dword v177, v[4:5], off
	v_lshl_add_u64 v[4:5], v[4:5], 0, s[8:9]
	global_load_dword v178, v[4:5], off
	v_lshl_add_u64 v[4:5], v[4:5], 0, s[8:9]
	global_load_dword v179, v[4:5], off
	v_lshl_add_u64 v[4:5], v[4:5], 0, s[8:9]
	global_load_dword v180, v[4:5], off
	v_lshl_add_u64 v[4:5], v[4:5], 0, s[8:9]
	global_load_dword v181, v[4:5], off
	v_lshl_add_u64 v[4:5], v[4:5], 0, s[8:9]
	global_load_dword v182, v[4:5], off
	v_lshl_add_u64 v[4:5], v[4:5], 0, s[8:9]
	global_load_dword v183, v[4:5], off
	v_lshl_add_u64 v[4:5], v[4:5], 0, s[8:9]
	global_load_dword v184, v[4:5], off
	v_lshl_add_u64 v[4:5], v[4:5], 0, s[8:9]
	global_load_dword v185, v[4:5], off
	v_lshl_add_u64 v[4:5], v[4:5], 0, s[8:9]
	global_load_dword v186, v[4:5], off
	v_lshl_add_u64 v[4:5], v[4:5], 0, s[8:9]
	global_load_dword v187, v[4:5], off
	v_lshl_add_u64 v[4:5], v[4:5], 0, s[8:9]
	global_load_dword v188, v[4:5], off
	v_lshl_add_u64 v[4:5], v[4:5], 0, s[8:9]
	global_load_dword v189, v[4:5], off
	v_lshl_add_u64 v[4:5], v[4:5], 0, s[8:9]
	global_load_dword v190, v[4:5], off
	v_lshl_add_u64 v[4:5], v[4:5], 0, s[8:9]
	global_load_dword v191, v[4:5], off
	v_lshl_add_u64 v[4:5], v[4:5], 0, s[8:9]
	s_waitcnt vmcnt(0)
	v_mul_f32_e32 v192, 0xbfb8aa3b, v176
	v_mul_f32_e32 v193, 0xbfb8aa3b, v177
	v_mul_f32_e32 v194, 0xbfb8aa3b, v178
	v_mul_f32_e32 v195, 0xbfb8aa3b, v179
	v_mul_f32_e32 v196, 0xbfb8aa3b, v180
	v_mul_f32_e32 v197, 0xbfb8aa3b, v181
	v_mul_f32_e32 v198, 0xbfb8aa3b, v182
	v_mul_f32_e32 v199, 0xbfb8aa3b, v183
	v_mul_f32_e32 v200, 0xbfb8aa3b, v184
	v_mul_f32_e32 v201, 0xbfb8aa3b, v185
	v_mul_f32_e32 v202, 0xbfb8aa3b, v186
	v_mul_f32_e32 v203, 0xbfb8aa3b, v187
	v_mul_f32_e32 v204, 0xbfb8aa3b, v188
	v_mul_f32_e32 v205, 0xbfb8aa3b, v189
	v_mul_f32_e32 v206, 0xbfb8aa3b, v190
	v_mul_f32_e32 v207, 0xbfb8aa3b, v191
	v_exp_f32_e32 v192, v192
	v_exp_f32_e32 v193, v193
	v_exp_f32_e32 v194, v194
	v_exp_f32_e32 v195, v195
	v_exp_f32_e32 v196, v196
	v_exp_f32_e32 v197, v197
	v_exp_f32_e32 v198, v198
	v_exp_f32_e32 v199, v199
	v_exp_f32_e32 v200, v200
	v_exp_f32_e32 v201, v201
	v_exp_f32_e32 v202, v202
	v_exp_f32_e32 v203, v203
	v_exp_f32_e32 v204, v204
	v_exp_f32_e32 v205, v205
	v_exp_f32_e32 v206, v206
	v_exp_f32_e32 v207, v207
	v_add_f32_e32 v192, 1.0, v192
	v_add_f32_e32 v193, 1.0, v193
	v_add_f32_e32 v194, 1.0, v194
	v_add_f32_e32 v195, 1.0, v195
	v_add_f32_e32 v196, 1.0, v196
	v_add_f32_e32 v197, 1.0, v197
	v_add_f32_e32 v198, 1.0, v198
	v_add_f32_e32 v199, 1.0, v199
	v_add_f32_e32 v200, 1.0, v200
	v_add_f32_e32 v201, 1.0, v201
	v_add_f32_e32 v202, 1.0, v202
	v_add_f32_e32 v203, 1.0, v203
	v_add_f32_e32 v204, 1.0, v204
	v_add_f32_e32 v205, 1.0, v205
	v_add_f32_e32 v206, 1.0, v206
	v_add_f32_e32 v207, 1.0, v207
	v_rcp_f32_e32 v192, v192
	v_rcp_f32_e32 v193, v193
	v_rcp_f32_e32 v194, v194
	v_rcp_f32_e32 v195, v195
	v_rcp_f32_e32 v196, v196
	v_rcp_f32_e32 v197, v197
	v_rcp_f32_e32 v198, v198
	v_rcp_f32_e32 v199, v199
	v_rcp_f32_e32 v200, v200
	v_rcp_f32_e32 v201, v201
	v_rcp_f32_e32 v202, v202
	v_rcp_f32_e32 v203, v203
	v_rcp_f32_e32 v204, v204
	v_rcp_f32_e32 v205, v205
	v_rcp_f32_e32 v206, v206
	v_rcp_f32_e32 v207, v207
	v_mul_f32_e32 v176, v176, v192
	v_mul_f32_e32 v177, v177, v193
	v_mul_f32_e32 v178, v178, v194
	v_mul_f32_e32 v179, v179, v195
	v_mul_f32_e32 v180, v180, v196
	v_mul_f32_e32 v181, v181, v197
	v_mul_f32_e32 v182, v182, v198
	v_mul_f32_e32 v183, v183, v199
	v_mul_f32_e32 v184, v184, v200
	v_mul_f32_e32 v185, v185, v201
	v_mul_f32_e32 v186, v186, v202
	v_mul_f32_e32 v187, v187, v203
	v_mul_f32_e32 v188, v188, v204
	v_mul_f32_e32 v189, v189, v205
	v_mul_f32_e32 v190, v190, v206
	v_mul_f32_e32 v191, v191, v207
	ds_write_b32 v6, v176
	ds_write_b32 v208, v177
	ds_write_b32 v6, v178 offset:4
	ds_write_b32 v208, v179 offset:4
	ds_write_b32 v6, v180 offset:8
	ds_write_b32 v208, v181 offset:8
	ds_write_b32 v6, v182 offset:12
	ds_write_b32 v208, v183 offset:12
	ds_write_b32 v6, v184 offset:16
	ds_write_b32 v208, v185 offset:16
	ds_write_b32 v6, v186 offset:20
	ds_write_b32 v208, v187 offset:20
	ds_write_b32 v6, v188 offset:24
	ds_write_b32 v208, v189 offset:24
	ds_write_b32 v6, v190 offset:28
	ds_write_b32 v208, v191 offset:28
	v_add_u32_e32 v6, 32, v6
	v_add_u32_e32 v208, 32, v208
	s_sub_u32 s3, s3, 1
	s_cmp_lg_u32 s3, 0
	s_cbranch_scc1 .Lsilu_pass
.LBB0_446:
	s_or_b64 exec, exec, s[10:11]
	v_ashrrev_i32_e32 v3, 6, v2
	v_lshl_add_u32 v1, s2, 3, v3
	s_movk_i32 s3, 0x1800
	v_and_b32_e32 v16, 63, v2
	v_cmp_gt_i32_e32 vcc, s3, v1
	s_waitcnt vmcnt(0) lgkmcnt(0)
	s_barrier
	s_and_saveexec_b64 s[10:11], vcc
	s_cbranch_execz .LBB0_453
	s_cmp_gt_u32 s75, 0xbf
	s_cbranch_scc1 .Lada2_skip
	s_load_dwordx4 s[44:47], s[0:1], 0x10
	v_readfirstlane_b32 s3, v3
	v_and_b32_e32 v4, 31, v16
	v_lshrrev_b32_e32 v5, 5, v16
	s_lshl_b32 s8, s3, 7
	v_lshl_add_u32 v6, v5, 6, s8
	v_mul_u32_u24_e32 v7, 0x84, v6
	v_lshl_add_u32 v7, v4, 2, v7
	v_mul_u32_u24_e32 v8, 0x6000, v6
	s_lshl_b32 s9, s75, 7
	v_lshl_add_u32 v9, v4, 2, s9
	v_add_u32_e32 v8, v8, v9
	v_mov_b32_e32 v9, 0
	s_waitcnt lgkmcnt(0)
	v_lshl_add_u64 v[8:9], s[44:45], 0, v[8:9]
	s_mov_b64 s[12:13], 0x6000
	v_mov_b64_e32 v[176:177], 0
	v_mov_b64_e32 v[178:179], 0
	v_mov_b64_e32 v[180:181], 0
	v_mov_b64_e32 v[182:183], 0
	v_mov_b64_e32 v[184:185], 0
	v_mov_b64_e32 v[186:187], 0
	v_mov_b64_e32 v[188:189], 0
	v_mov_b64_e32 v[190:191], 0
	global_load_dword v192, v[8:9], off
	v_lshl_add_u64 v[8:9], v[8:9], 0, s[12:13]
	global_load_dword v193, v[8:9], off
	v_lshl_add_u64 v[8:9], v[8:9], 0, s[12:13]
	global_load_dword v194, v[8:9], off
	v_lshl_add_u64 v[8:9], v[8:9], 0, s[12:13]
	global_load_dword v195, v[8:9], off
	v_lshl_add_u64 v[8:9], v[8:9], 0, s[12:13]
	global_load_dword v196, v[8:9], off
	v_lshl_add_u64 v[8:9], v[8:9], 0, s[12:13]
	global_load_dword v197, v[8:9], off
	v_lshl_add_u64 v[8:9], v[8:9], 0, s[12:13]
	global_load_dword v198, v[8:9], off
	v_lshl_add_u64 v[8:9], v[8:9], 0, s[12:13]
	global_load_dword v199, v[8:9], off
	v_lshl_add_u64 v[8:9], v[8:9], 0, s[12:13]
	global_load_dword v200, v[8:9], off
	v_lshl_add_u64 v[8:9], v[8:9], 0, s[12:13]
	global_load_dword v201, v[8:9], off
	v_lshl_add_u64 v[8:9], v[8:9], 0, s[12:13]
	global_load_dword v202, v[8:9], off
	v_lshl_add_u64 v[8:9], v[8:9], 0, s[12:13]
	global_load_dword v203, v[8:9], off
	v_lshl_add_u64 v[8:9], v[8:9], 0, s[12:13]
	global_load_dword v204, v[8:9], off
	v_lshl_add_u64 v[8:9], v[8:9], 0, s[12:13]
	global_load_dword v205, v[8:9], off
	v_lshl_add_u64 v[8:9], v[8:9], 0, s[12:13]
	global_load_dword v206, v[8:9], off
	v_lshl_add_u64 v[8:9], v[8:9], 0, s[12:13]
	global_load_dword v207, v[8:9], off
	v_lshl_add_u64 v[8:9], v[8:9], 0, s[12:13]
	global_load_dword v208, v[8:9], off
	v_lshl_add_u64 v[8:9], v[8:9], 0, s[12:13]
	global_load_dword v209, v[8:9], off
	v_lshl_add_u64 v[8:9], v[8:9], 0, s[12:13]
	global_load_dword v210, v[8:9], off
	v_lshl_add_u64 v[8:9], v[8:9], 0, s[12:13]
	global_load_dword v211, v[8:9], off
	v_lshl_add_u64 v[8:9], v[8:9], 0, s[12:13]
	global_load_dword v212, v[8:9], off
	v_lshl_add_u64 v[8:9], v[8:9], 0, s[12:13]
	global_load_dword v213, v[8:9], off
	v_lshl_add_u64 v[8:9], v[8:9], 0, s[12:13]
	global_load_dword v214, v[8:9], off
	v_lshl_add_u64 v[8:9], v[8:9], 0, s[12:13]
	global_load_dword v215, v[8:9], off
	v_lshl_add_u64 v[8:9], v[8:9], 0, s[12:13]
	global_load_dword v216, v[8:9], off
	v_lshl_add_u64 v[8:9], v[8:9], 0, s[12:13]
	global_load_dword v217, v[8:9], off
	v_lshl_add_u64 v[8:9], v[8:9], 0, s[12:13]
	global_load_dword v218, v[8:9], off
	v_lshl_add_u64 v[8:9], v[8:9], 0, s[12:13]
	global_load_dword v219, v[8:9], off
	v_lshl_add_u64 v[8:9], v[8:9], 0, s[12:13]
	global_load_dword v220, v[8:9], off
	v_lshl_add_u64 v[8:9], v[8:9], 0, s[12:13]
	global_load_dword v221, v[8:9], off
	v_lshl_add_u64 v[8:9], v[8:9], 0, s[12:13]
	global_load_dword v222, v[8:9], off
	v_lshl_add_u64 v[8:9], v[8:9], 0, s[12:13]
	global_load_dword v223, v[8:9], off
	v_lshl_add_u64 v[8:9], v[8:9], 0, s[12:13]
	global_load_dword v15, v[8:9], off
	v_lshl_add_u64 v[8:9], v[8:9], 0, s[12:13]
	global_load_dword v17, v[8:9], off
	v_lshl_add_u64 v[8:9], v[8:9], 0, s[12:13]
	global_load_dword v18, v[8:9], off
	v_lshl_add_u64 v[8:9], v[8:9], 0, s[12:13]
	global_load_dword v19, v[8:9], off
	v_lshl_add_u64 v[8:9], v[8:9], 0, s[12:13]
	global_load_dword v20, v[8:9], off
	v_lshl_add_u64 v[8:9], v[8:9], 0, s[12:13]
	global_load_dword v21, v[8:9], off
	v_lshl_add_u64 v[8:9], v[8:9], 0, s[12:13]
	global_load_dword v22, v[8:9], off
	v_lshl_add_u64 v[8:9], v[8:9], 0, s[12:13]
	global_load_dword v23, v[8:9], off
	v_lshl_add_u64 v[8:9], v[8:9], 0, s[12:13]
	global_load_dword v24, v[8:9], off
	v_lshl_add_u64 v[8:9], v[8:9], 0, s[12:13]
	global_load_dword v25, v[8:9], off
	v_lshl_add_u64 v[8:9], v[8:9], 0, s[12:13]
	global_load_dword v26, v[8:9], off
	v_lshl_add_u64 v[8:9], v[8:9], 0, s[12:13]
	global_load_dword v27, v[8:9], off
	v_lshl_add_u64 v[8:9], v[8:9], 0, s[12:13]
	global_load_dword v28, v[8:9], off
	v_lshl_add_u64 v[8:9], v[8:9], 0, s[12:13]
	global_load_dword v29, v[8:9], off
	v_lshl_add_u64 v[8:9], v[8:9], 0, s[12:13]
	global_load_dword v30, v[8:9], off
	v_lshl_add_u64 v[8:9], v[8:9], 0, s[12:13]
	global_load_dword v31, v[8:9], off
	v_lshl_add_u64 v[8:9], v[8:9], 0, s[12:13]
	s_waitcnt vmcnt(32)
	ds_read_b32 v224, v7 offset:0
	ds_read_b32 v225, v7 offset:132
	ds_read_b32 v226, v7 offset:264
	ds_read_b32 v227, v7 offset:396
	ds_read_b32 v228, v7 offset:528
	ds_read_b32 v229, v7 offset:660
	ds_read_b32 v230, v7 offset:792
	ds_read_b32 v231, v7 offset:924
	s_waitcnt lgkmcnt(7)
	v_mfma_f32_32x32x2_f32 v[176:191], v224, v192, v[176:191]
	s_waitcnt lgkmcnt(6)
	v_mfma_f32_32x32x2_f32 v[176:191], v225, v193, v[176:191]
	s_waitcnt lgkmcnt(5)
	v_mfma_f32_32x32x2_f32 v[176:191], v226, v194, v[176:191]
	s_waitcnt lgkmcnt(4)
	v_mfma_f32_32x32x2_f32 v[176:191], v227, v195, v[176:191]
	s_waitcnt lgkmcnt(3)
	v_mfma_f32_32x32x2_f32 v[176:191], v228, v196, v[176:191]
	s_waitcnt lgkmcnt(2)
	v_mfma_f32_32x32x2_f32 v[176:191], v229, v197, v[176:191]
	s_waitcnt lgkmcnt(1)
	v_mfma_f32_32x32x2_f32 v[176:191], v230, v198, v[176:191]
	s_waitcnt lgkmcnt(0)
	v_mfma_f32_32x32x2_f32 v[176:191], v231, v199, v[176:191]
	ds_read_b32 v224, v7 offset:1056
	ds_read_b32 v225, v7 offset:1188
	ds_read_b32 v226, v7 offset:1320
	ds_read_b32 v227, v7 offset:1452
	ds_read_b32 v228, v7 offset:1584
	ds_read_b32 v229, v7 offset:1716
	ds_read_b32 v230, v7 offset:1848
	ds_read_b32 v231, v7 offset:1980
	s_waitcnt lgkmcnt(7)
	v_mfma_f32_32x32x2_f32 v[176:191], v224, v200, v[176:191]
	s_waitcnt lgkmcnt(6)
	v_mfma_f32_32x32x2_f32 v[176:191], v225, v201, v[176:191]
	s_waitcnt lgkmcnt(5)
	v_mfma_f32_32x32x2_f32 v[176:191], v226, v202, v[176:191]
	s_waitcnt lgkmcnt(4)
	v_mfma_f32_32x32x2_f32 v[176:191], v227, v203, v[176:191]
	s_waitcnt lgkmcnt(3)
	v_mfma_f32_32x32x2_f32 v[176:191], v228, v204, v[176:191]
	s_waitcnt lgkmcnt(2)
	v_mfma_f32_32x32x2_f32 v[176:191], v229, v205, v[176:191]
	s_waitcnt lgkmcnt(1)
	v_mfma_f32_32x32x2_f32 v[176:191], v230, v206, v[176:191]
	s_waitcnt lgkmcnt(0)
	v_mfma_f32_32x32x2_f32 v[176:191], v231, v207, v[176:191]
	global_load_dword v192, v[8:9], off
	v_lshl_add_u64 v[8:9], v[8:9], 0, s[12:13]
	global_load_dword v193, v[8:9], off
	v_lshl_add_u64 v[8:9], v[8:9], 0, s[12:13]
	global_load_dword v194, v[8:9], off
	v_lshl_add_u64 v[8:9], v[8:9], 0, s[12:13]
	global_load_dword v195, v[8:9], off
	v_lshl_add_u64 v[8:9], v[8:9], 0, s[12:13]
	global_load_dword v196, v[8:9], off
	v_lshl_add_u64 v[8:9], v[8:9], 0, s[12:13]
	global_load_dword v197, v[8:9], off
	v_lshl_add_u64 v[8:9], v[8:9], 0, s[12:13]
	global_load_dword v198, v[8:9], off
	v_lshl_add_u64 v[8:9], v[8:9], 0, s[12:13]
	global_load_dword v199, v[8:9], off
	v_lshl_add_u64 v[8:9], v[8:9], 0, s[12:13]
	global_load_dword v200, v[8:9], off
	v_lshl_add_u64 v[8:9], v[8:9], 0, s[12:13]
	global_load_dword v201, v[8:9], off
	v_lshl_add_u64 v[8:9], v[8:9], 0, s[12:13]
	global_load_dword v202, v[8:9], off
	v_lshl_add_u64 v[8:9], v[8:9], 0, s[12:13]
	global_load_dword v203, v[8:9], off
	v_lshl_add_u64 v[8:9], v[8:9], 0, s[12:13]
	global_load_dword v204, v[8:9], off
	v_lshl_add_u64 v[8:9], v[8:9], 0, s[12:13]
	global_load_dword v205, v[8:9], off
	v_lshl_add_u64 v[8:9], v[8:9], 0, s[12:13]
	global_load_dword v206, v[8:9], off
	v_lshl_add_u64 v[8:9], v[8:9], 0, s[12:13]
	global_load_dword v207, v[8:9], off
	v_lshl_add_u64 v[8:9], v[8:9], 0, s[12:13]
	s_waitcnt vmcnt(32)
	ds_read_b32 v224, v7 offset:2112
	ds_read_b32 v225, v7 offset:2244
	ds_read_b32 v226, v7 offset:2376
	ds_read_b32 v227, v7 offset:2508
	ds_read_b32 v228, v7 offset:2640
	ds_read_b32 v229, v7 offset:2772
	ds_read_b32 v230, v7 offset:2904
	ds_read_b32 v231, v7 offset:3036
	s_waitcnt lgkmcnt(7)
	v_mfma_f32_32x32x2_f32 v[176:191], v224, v208, v[176:191]
	s_waitcnt lgkmcnt(6)
	v_mfma_f32_32x32x2_f32 v[176:191], v225, v209, v[176:191]
	s_waitcnt lgkmcnt(5)
	v_mfma_f32_32x32x2_f32 v[176:191], v226, v210, v[176:191]
	s_waitcnt lgkmcnt(4)
	v_mfma_f32_32x32x2_f32 v[176:191], v227, v211, v[176:191]
	s_waitcnt lgkmcnt(3)
	v_mfma_f32_32x32x2_f32 v[176:191], v228, v212, v[176:191]
	s_waitcnt lgkmcnt(2)
	v_mfma_f32_32x32x2_f32 v[176:191], v229, v213, v[176:191]
	s_waitcnt lgkmcnt(1)
	v_mfma_f32_32x32x2_f32 v[176:191], v230, v214, v[176:191]
	s_waitcnt lgkmcnt(0)
	v_mfma_f32_32x32x2_f32 v[176:191], v231, v215, v[176:191]
	ds_read_b32 v224, v7 offset:3168
	ds_read_b32 v225, v7 offset:3300
	ds_read_b32 v226, v7 offset:3432
	ds_read_b32 v227, v7 offset:3564
	ds_read_b32 v228, v7 offset:3696
	ds_read_b32 v229, v7 offset:3828
	ds_read_b32 v230, v7 offset:3960
	ds_read_b32 v231, v7 offset:4092
	s_waitcnt lgkmcnt(7)
	v_mfma_f32_32x32x2_f32 v[176:191], v224, v216, v[176:191]
	s_waitcnt lgkmcnt(6)
	v_mfma_f32_32x32x2_f32 v[176:191], v225, v217, v[176:191]
	s_waitcnt lgkmcnt(5)
	v_mfma_f32_32x32x2_f32 v[176:191], v226, v218, v[176:191]
	s_waitcnt lgkmcnt(4)
	v_mfma_f32_32x32x2_f32 v[176:191], v227, v219, v[176:191]
	s_waitcnt lgkmcnt(3)
	v_mfma_f32_32x32x2_f32 v[176:191], v228, v220, v[176:191]
	s_waitcnt lgkmcnt(2)
	v_mfma_f32_32x32x2_f32 v[176:191], v229, v221, v[176:191]
	s_waitcnt lgkmcnt(1)
	v_mfma_f32_32x32x2_f32 v[176:191], v230, v222, v[176:191]
	s_waitcnt lgkmcnt(0)
	v_mfma_f32_32x32x2_f32 v[176:191], v231, v223, v[176:191]
	s_waitcnt vmcnt(16)
	ds_read_b32 v224, v7 offset:4224
	ds_read_b32 v225, v7 offset:4356
	ds_read_b32 v226, v7 offset:4488
	ds_read_b32 v227, v7 offset:4620
	ds_read_b32 v228, v7 offset:4752
	ds_read_b32 v229, v7 offset:4884
	ds_read_b32 v230, v7 offset:5016
	ds_read_b32 v231, v7 offset:5148
	s_waitcnt lgkmcnt(7)
	v_mfma_f32_32x32x2_f32 v[176:191], v224, v15, v[176:191]
	s_waitcnt lgkmcnt(6)
	v_mfma_f32_32x32x2_f32 v[176:191], v225, v17, v[176:191]
	s_waitcnt lgkmcnt(5)
	v_mfma_f32_32x32x2_f32 v[176:191], v226, v18, v[176:191]
	s_waitcnt lgkmcnt(4)
	v_mfma_f32_32x32x2_f32 v[176:191], v227, v19, v[176:191]
	s_waitcnt lgkmcnt(3)
	v_mfma_f32_32x32x2_f32 v[176:191], v228, v20, v[176:191]
	s_waitcnt lgkmcnt(2)
	v_mfma_f32_32x32x2_f32 v[176:191], v229, v21, v[176:191]
	s_waitcnt lgkmcnt(1)
	v_mfma_f32_32x32x2_f32 v[176:191], v230, v22, v[176:191]
	s_waitcnt lgkmcnt(0)
	v_mfma_f32_32x32x2_f32 v[176:191], v231, v23, v[176:191]
	ds_read_b32 v224, v7 offset:5280
	ds_read_b32 v225, v7 offset:5412
	ds_read_b32 v226, v7 offset:5544
	ds_read_b32 v227, v7 offset:5676
	ds_read_b32 v228, v7 offset:5808
	ds_read_b32 v229, v7 offset:5940
	ds_read_b32 v230, v7 offset:6072
	ds_read_b32 v231, v7 offset:6204
	s_waitcnt lgkmcnt(7)
	v_mfma_f32_32x32x2_f32 v[176:191], v224, v24, v[176:191]
	s_waitcnt lgkmcnt(6)
	v_mfma_f32_32x32x2_f32 v[176:191], v225, v25, v[176:191]
	s_waitcnt lgkmcnt(5)
	v_mfma_f32_32x32x2_f32 v[176:191], v226, v26, v[176:191]
	s_waitcnt lgkmcnt(4)
	v_mfma_f32_32x32x2_f32 v[176:191], v227, v27, v[176:191]
	s_waitcnt lgkmcnt(3)
	v_mfma_f32_32x32x2_f32 v[176:191], v228, v28, v[176:191]
	s_waitcnt lgkmcnt(2)
	v_mfma_f32_32x32x2_f32 v[176:191], v229, v29, v[176:191]
	s_waitcnt lgkmcnt(1)
	v_mfma_f32_32x32x2_f32 v[176:191], v230, v30, v[176:191]
	s_waitcnt lgkmcnt(0)
	v_mfma_f32_32x32x2_f32 v[176:191], v231, v31, v[176:191]
	s_waitcnt vmcnt(0)
	ds_read_b32 v224, v7 offset:6336
	ds_read_b32 v225, v7 offset:6468
	ds_read_b32 v226, v7 offset:6600
	ds_read_b32 v227, v7 offset:6732
	ds_read_b32 v228, v7 offset:6864
	ds_read_b32 v229, v7 offset:6996
	ds_read_b32 v230, v7 offset:7128
	ds_read_b32 v231, v7 offset:7260
	s_waitcnt lgkmcnt(7)
	v_mfma_f32_32x32x2_f32 v[176:191], v224, v192, v[176:191]
	s_waitcnt lgkmcnt(6)
	v_mfma_f32_32x32x2_f32 v[176:191], v225, v193, v[176:191]
	s_waitcnt lgkmcnt(5)
	v_mfma_f32_32x32x2_f32 v[176:191], v226, v194, v[176:191]
	s_waitcnt lgkmcnt(4)
	v_mfma_f32_32x32x2_f32 v[176:191], v227, v195, v[176:191]
	s_waitcnt lgkmcnt(3)
	v_mfma_f32_32x32x2_f32 v[176:191], v228, v196, v[176:191]
	s_waitcnt lgkmcnt(2)
	v_mfma_f32_32x32x2_f32 v[176:191], v229, v197, v[176:191]
	s_waitcnt lgkmcnt(1)
	v_mfma_f32_32x32x2_f32 v[176:191], v230, v198, v[176:191]
	s_waitcnt lgkmcnt(0)
	v_mfma_f32_32x32x2_f32 v[176:191], v231, v199, v[176:191]
	ds_read_b32 v224, v7 offset:7392
	ds_read_b32 v225, v7 offset:7524
	ds_read_b32 v226, v7 offset:7656
	ds_read_b32 v227, v7 offset:7788
	ds_read_b32 v228, v7 offset:7920
	ds_read_b32 v229, v7 offset:8052
	ds_read_b32 v230, v7 offset:8184
	ds_read_b32 v231, v7 offset:8316
	s_waitcnt lgkmcnt(7)
	v_mfma_f32_32x32x2_f32 v[176:191], v224, v200, v[176:191]
	s_waitcnt lgkmcnt(6)
	v_mfma_f32_32x32x2_f32 v[176:191], v225, v201, v[176:191]
	s_waitcnt lgkmcnt(5)
	v_mfma_f32_32x32x2_f32 v[176:191], v226, v202, v[176:191]
	s_waitcnt lgkmcnt(4)
	v_mfma_f32_32x32x2_f32 v[176:191], v227, v203, v[176:191]
	s_waitcnt lgkmcnt(3)
	v_mfma_f32_32x32x2_f32 v[176:191], v228, v204, v[176:191]
	s_waitcnt lgkmcnt(2)
	v_mfma_f32_32x32x2_f32 v[176:191], v229, v205, v[176:191]
	s_waitcnt lgkmcnt(1)
	v_mfma_f32_32x32x2_f32 v[176:191], v230, v206, v[176:191]
	s_waitcnt lgkmcnt(0)
	v_mfma_f32_32x32x2_f32 v[176:191], v231, v207, v[176:191]
	s_nop 15
	s_nop 3
	s_barrier
	s_lshl_b32 s8, s3, 12
	v_lshl_add_u32 v6, v5, 9, s8
	v_lshl_add_u32 v6, v4, 2, v6
	ds_write_b32 v6, v176
	ds_write_b32 v6, v177 offset:128
	ds_write_b32 v6, v178 offset:256
	ds_write_b32 v6, v179 offset:384
	ds_write_b32 v6, v180 offset:1024
	ds_write_b32 v6, v181 offset:1152
	ds_write_b32 v6, v182 offset:1280
	ds_write_b32 v6, v183 offset:1408
	ds_write_b32 v6, v184 offset:2048
	ds_write_b32 v6, v185 offset:2176
	ds_write_b32 v6, v186 offset:2304
	ds_write_b32 v6, v187 offset:2432
	ds_write_b32 v6, v188 offset:3072
	ds_write_b32 v6, v189 offset:3200
	ds_write_b32 v6, v190 offset:3328
	ds_write_b32 v6, v191 offset:3456
	s_waitcnt lgkmcnt(0)
	s_barrier
	v_lshlrev_b32_e32 v6, 2, v2
	ds_read_b32 v192, v6 offset:0
	ds_read_b32 v193, v6 offset:4096
	ds_read_b32 v194, v6 offset:8192
	ds_read_b32 v195, v6 offset:12288
	ds_read_b32 v196, v6 offset:16384
	ds_read_b32 v197, v6 offset:20480
	ds_read_b32 v198, v6 offset:24576
	ds_read_b32 v199, v6 offset:28672
	ds_read_b32 v200, v6 offset:2048
	ds_read_b32 v201, v6 offset:6144
	ds_read_b32 v202, v6 offset:10240
	ds_read_b32 v203, v6 offset:14336
	ds_read_b32 v204, v6 offset:18432
	ds_read_b32 v205, v6 offset:22528
	ds_read_b32 v206, v6 offset:26624
	ds_read_b32 v207, v6 offset:30720
	v_and_b32_e32 v4, 31, v2
	v_lshrrev_b32_e32 v5, 5, v2
	v_lshl_add_u32 v10, v4, 2, s9
	v_mov_b32_e32 v11, 0
	v_lshl_add_u64 v[12:13], s[46:47], 0, v[10:11]
	global_load_dword v14, v[12:13], off
	v_mul_u32_u24_e32 v9, 0x6000, v5
	v_add_u32_e32 v10, v10, v9
	v_lshl_add_u64 v[12:13], s[6:7], 0, v[10:11]
	s_waitcnt lgkmcnt(0)
	v_add_f32_e32 v192, v192, v193
	v_add_f32_e32 v194, v194, v195
	v_add_f32_e32 v196, v196, v197
	v_add_f32_e32 v198, v198, v199
	v_add_f32_e32 v192, v192, v194
	v_add_f32_e32 v196, v196, v198
	v_add_f32_e32 v192, v192, v196
	v_add_f32_e32 v200, v200, v201
	v_add_f32_e32 v202, v202, v203
	v_add_f32_e32 v204, v204, v205
	v_add_f32_e32 v206, v206, v207
	v_add_f32_e32 v200, v200, v202
	v_add_f32_e32 v204, v204, v206
	v_add_f32_e32 v200, v200, v204
	s_waitcnt vmcnt(0)
	v_add_f32_e32 v192, v192, v14
	v_add_f32_e32 v200, v200, v14
	global_store_dword v[12:13], v192, off
	s_mov_b64 s[12:13], 0x60000
	v_lshl_add_u64 v[12:13], v[12:13], 0, s[12:13]
	global_store_dword v[12:13], v200, off
.Lada2_skip:
.LBB0_453:
	s_or_b64 exec, exec, s[10:11]
	s_waitcnt vmcnt(0)
	v_cmp_eq_u32_e32 vcc, 0, v2
	s_barrier
	s_and_saveexec_b64 s[10:11], vcc
	s_cbranch_execz .LBB0_456
	s_mov_b64 s[12:13], exec
	v_mbcnt_lo_u32_b32 v4, s12, 0
	buffer_wbl2 sc1
	s_waitcnt vmcnt(0)
	s_waitcnt vmcnt(0)
	v_mbcnt_hi_u32_b32 v4, s13, v4
	v_cmp_eq_u32_e32 vcc, 0, v4
	s_and_b64 s[8:9], exec, vcc
	s_mov_b64 exec, s[8:9]
	s_cbranch_execz .LBB0_456
	s_bcnt1_i32_b64 s3, s[12:13]
	v_mov_b32_e32 v4, s3
	global_atomic_add v0, v4, s[66:67]
